# the nine GEMM K-loop heads aligned to 64 bytes (.p2align 6)
# speedup vs baseline: 1.0008x; 1.0008x over previous
.LBB0_394:
	s_ashr_i32 s17, s16, 31
	s_lshl_b64 s[18:19], s[16:17], 19
	s_add_u32 s18, s70, s18
	s_addc_u32 s19, s71, s19
	s_and_b64 s[20:21], s[0:1], exec
	s_cselect_b32 s17, s19, s23
	s_cselect_b32 s41, s18, s22
	s_ashr_i32 s15, s14, 31
	v_readlane_b32 s44, v253, 24
	s_lshl_b64 s[20:21], s[14:15], 19
	v_readlane_b32 s48, v253, 28
	v_readlane_b32 s49, v253, 29
	s_add_u32 s20, s48, s20
	s_addc_u32 s21, s49, s21
	s_and_b64 s[26:27], s[0:1], exec
	s_cselect_b32 s15, s21, s25
	s_cselect_b32 s42, s20, s24
	s_add_u32 s22, s22, 0x40080
	s_addc_u32 s23, s23, 0
	v_readlane_b32 s45, v253, 25
	s_add_u32 s43, s24, 0x100
	v_mov_b32_e32 v2, 0
	s_addc_u32 s44, s25, 0
	s_mov_b32 s45, -2
	v_mov_b32_e32 v3, v2
	v_mov_b32_e32 v4, v2
	v_mov_b32_e32 v5, v2
	v_mov_b32_e32 v6, v2
	v_mov_b32_e32 v7, v2
	v_mov_b32_e32 v8, v2
	v_mov_b32_e32 v9, v2
	v_mov_b32_e32 v10, v2
	v_mov_b32_e32 v11, v2
	v_mov_b32_e32 v12, v2
	v_mov_b32_e32 v13, v2
	v_mov_b32_e32 v14, v2
	v_mov_b32_e32 v15, v2
	v_mov_b32_e32 v16, v2
	v_mov_b32_e32 v17, v2
	v_mov_b32_e32 v26, v2
	v_mov_b32_e32 v27, v2
	v_mov_b32_e32 v28, v2
	v_mov_b32_e32 v29, v2
	v_mov_b32_e32 v30, v2
	v_mov_b32_e32 v31, v2
	v_mov_b32_e32 v32, v2
	v_mov_b32_e32 v33, v2
	v_mov_b32_e32 v42, v2
	v_mov_b32_e32 v43, v2
	v_mov_b32_e32 v44, v2
	v_mov_b32_e32 v45, v2
	v_mov_b32_e32 v46, v2
	v_mov_b32_e32 v47, v2
	v_mov_b32_e32 v48, v2
	v_mov_b32_e32 v49, v2
	v_mov_b32_e32 v18, v2
	v_mov_b32_e32 v19, v2
	v_mov_b32_e32 v20, v2
	v_mov_b32_e32 v21, v2
	v_mov_b32_e32 v22, v2
	v_mov_b32_e32 v23, v2
	v_mov_b32_e32 v24, v2
	v_mov_b32_e32 v25, v2
	v_mov_b32_e32 v34, v2
	v_mov_b32_e32 v35, v2
	v_mov_b32_e32 v36, v2
	v_mov_b32_e32 v37, v2
	v_mov_b32_e32 v38, v2
	v_mov_b32_e32 v39, v2
	v_mov_b32_e32 v40, v2
	v_mov_b32_e32 v41, v2
	v_mov_b32_e32 v50, v2
	v_mov_b32_e32 v51, v2
	v_mov_b32_e32 v52, v2
	v_mov_b32_e32 v53, v2
	v_mov_b32_e32 v54, v2
	v_mov_b32_e32 v55, v2
	v_mov_b32_e32 v56, v2
	v_mov_b32_e32 v57, v2
	v_mov_b32_e32 v58, v2
	v_mov_b32_e32 v59, v2
	v_mov_b32_e32 v60, v2
	v_mov_b32_e32 v61, v2
	v_mov_b32_e32 v62, v2
	v_mov_b32_e32 v63, v2
	v_mov_b32_e32 v64, v2
	v_mov_b32_e32 v65, v2
	v_mov_b32_e32 v66, v2
	v_mov_b32_e32 v67, v2
	v_mov_b32_e32 v68, v2
	v_mov_b32_e32 v69, v2
	v_mov_b32_e32 v70, v2
	v_mov_b32_e32 v71, v2
	v_mov_b32_e32 v72, v2
	v_mov_b32_e32 v73, v2
	v_mov_b32_e32 v74, v2
	v_mov_b32_e32 v75, v2
	v_mov_b32_e32 v76, v2
	v_mov_b32_e32 v77, v2
	v_mov_b32_e32 v78, v2
	v_mov_b32_e32 v79, v2
	v_mov_b32_e32 v80, v2
	v_mov_b32_e32 v81, v2
	v_mov_b32_e32 v90, v2
	v_mov_b32_e32 v91, v2
	v_mov_b32_e32 v92, v2
	v_mov_b32_e32 v93, v2
	v_mov_b32_e32 v94, v2
	v_mov_b32_e32 v95, v2
	v_mov_b32_e32 v96, v2
	v_mov_b32_e32 v97, v2
	v_mov_b32_e32 v106, v2
	v_mov_b32_e32 v107, v2
	v_mov_b32_e32 v108, v2
	v_mov_b32_e32 v109, v2
	v_mov_b32_e32 v110, v2
	v_mov_b32_e32 v111, v2
	v_mov_b32_e32 v112, v2
	v_mov_b32_e32 v113, v2
	v_mov_b32_e32 v82, v2
	v_mov_b32_e32 v83, v2
	v_mov_b32_e32 v84, v2
	v_mov_b32_e32 v85, v2
	v_mov_b32_e32 v86, v2
	v_mov_b32_e32 v87, v2
	v_mov_b32_e32 v88, v2
	v_mov_b32_e32 v89, v2
	v_mov_b32_e32 v98, v2
	v_mov_b32_e32 v99, v2
	v_mov_b32_e32 v100, v2
	v_mov_b32_e32 v101, v2
	v_mov_b32_e32 v102, v2
	v_mov_b32_e32 v103, v2
	v_mov_b32_e32 v104, v2
	v_mov_b32_e32 v105, v2
	v_mov_b32_e32 v114, v2
	v_mov_b32_e32 v115, v2
	v_mov_b32_e32 v116, v2
	v_mov_b32_e32 v117, v2
	v_mov_b32_e32 v118, v2
	v_mov_b32_e32 v119, v2
	v_mov_b32_e32 v120, v2
	v_mov_b32_e32 v121, v2
	v_mov_b32_e32 v122, v2
	v_mov_b32_e32 v123, v2
	v_mov_b32_e32 v124, v2
	v_mov_b32_e32 v125, v2
	v_mov_b32_e32 v126, v2
	v_mov_b32_e32 v127, v2
	v_mov_b32_e32 v128, v2
	v_mov_b32_e32 v129, v2
	v_readlane_b32 s46, v253, 26
	v_readlane_b32 s47, v253, 27
	v_readlane_b32 s50, v253, 30
	v_readlane_b32 s51, v253, 31
	v_readlane_b32 s52, v253, 32
	v_readlane_b32 s53, v253, 33
	v_readlane_b32 s54, v253, 34
	v_readlane_b32 s55, v253, 35
	v_readlane_b32 s56, v253, 36
	v_readlane_b32 s57, v253, 37
	v_readlane_b32 s58, v253, 38
	v_readlane_b32 s59, v253, 39
	.p2align	6

.LBB0_418:
	s_ashr_i32 s17, s16, 31
	s_lshl_b64 s[10:11], s[16:17], 19
	s_add_u32 s18, s72, s10
	s_addc_u32 s19, s73, s11
	s_and_b64 s[10:11], s[12:13], exec
	s_cselect_b32 s10, s19, s23
	s_cselect_b32 s11, s18, s22
	s_ashr_i32 s15, s14, 31
	v_readlane_b32 s44, v253, 24
	s_lshl_b64 s[20:21], s[14:15], 19
	v_readlane_b32 s58, v253, 38
	v_readlane_b32 s59, v253, 39
	s_add_u32 s20, s58, s20
	s_addc_u32 s21, s59, s21
	s_and_b64 s[26:27], s[12:13], exec
	s_cselect_b32 s15, s21, s25
	s_cselect_b32 s17, s20, s24
	s_add_u32 s22, s22, 0x40080
	s_addc_u32 s23, s23, 0
	s_add_u32 s41, s24, 0x100
	v_mov_b32_e32 v2, 0
	s_addc_u32 s42, s25, 0
	s_mov_b32 s43, -2
	v_mov_b32_e32 v3, v2
	v_mov_b32_e32 v4, v2
	v_mov_b32_e32 v5, v2
	v_mov_b32_e32 v6, v2
	v_mov_b32_e32 v7, v2
	v_mov_b32_e32 v8, v2
	v_mov_b32_e32 v9, v2
	v_mov_b32_e32 v10, v2
	v_mov_b32_e32 v11, v2
	v_mov_b32_e32 v12, v2
	v_mov_b32_e32 v13, v2
	v_mov_b32_e32 v14, v2
	v_mov_b32_e32 v15, v2
	v_mov_b32_e32 v16, v2
	v_mov_b32_e32 v17, v2
	v_mov_b32_e32 v26, v2
	v_mov_b32_e32 v27, v2
	v_mov_b32_e32 v28, v2
	v_mov_b32_e32 v29, v2
	v_mov_b32_e32 v30, v2
	v_mov_b32_e32 v31, v2
	v_mov_b32_e32 v32, v2
	v_mov_b32_e32 v33, v2
	v_mov_b32_e32 v42, v2
	v_mov_b32_e32 v43, v2
	v_mov_b32_e32 v44, v2
	v_mov_b32_e32 v45, v2
	v_mov_b32_e32 v46, v2
	v_mov_b32_e32 v47, v2
	v_mov_b32_e32 v48, v2
	v_mov_b32_e32 v49, v2
	v_mov_b32_e32 v18, v2
	v_mov_b32_e32 v19, v2
	v_mov_b32_e32 v20, v2
	v_mov_b32_e32 v21, v2
	v_mov_b32_e32 v22, v2
	v_mov_b32_e32 v23, v2
	v_mov_b32_e32 v24, v2
	v_mov_b32_e32 v25, v2
	v_mov_b32_e32 v34, v2
	v_mov_b32_e32 v35, v2
	v_mov_b32_e32 v36, v2
	v_mov_b32_e32 v37, v2
	v_mov_b32_e32 v38, v2
	v_mov_b32_e32 v39, v2
	v_mov_b32_e32 v40, v2
	v_mov_b32_e32 v41, v2
	v_mov_b32_e32 v50, v2
	v_mov_b32_e32 v51, v2
	v_mov_b32_e32 v52, v2
	v_mov_b32_e32 v53, v2
	v_mov_b32_e32 v54, v2
	v_mov_b32_e32 v55, v2
	v_mov_b32_e32 v56, v2
	v_mov_b32_e32 v57, v2
	v_mov_b32_e32 v58, v2
	v_mov_b32_e32 v59, v2
	v_mov_b32_e32 v60, v2
	v_mov_b32_e32 v61, v2
	v_mov_b32_e32 v62, v2
	v_mov_b32_e32 v63, v2
	v_mov_b32_e32 v64, v2
	v_mov_b32_e32 v65, v2
	v_mov_b32_e32 v66, v2
	v_mov_b32_e32 v67, v2
	v_mov_b32_e32 v68, v2
	v_mov_b32_e32 v69, v2
	v_mov_b32_e32 v70, v2
	v_mov_b32_e32 v71, v2
	v_mov_b32_e32 v72, v2
	v_mov_b32_e32 v73, v2
	v_mov_b32_e32 v74, v2
	v_mov_b32_e32 v75, v2
	v_mov_b32_e32 v76, v2
	v_mov_b32_e32 v77, v2
	v_mov_b32_e32 v78, v2
	v_mov_b32_e32 v79, v2
	v_mov_b32_e32 v80, v2
	v_mov_b32_e32 v81, v2
	v_mov_b32_e32 v86, v2
	v_mov_b32_e32 v87, v2
	v_mov_b32_e32 v88, v2
	v_mov_b32_e32 v89, v2
	v_mov_b32_e32 v94, v2
	v_mov_b32_e32 v95, v2
	v_mov_b32_e32 v96, v2
	v_mov_b32_e32 v97, v2
	v_mov_b32_e32 v102, v2
	v_mov_b32_e32 v103, v2
	v_mov_b32_e32 v104, v2
	v_mov_b32_e32 v105, v2
	v_mov_b32_e32 v110, v2
	v_mov_b32_e32 v111, v2
	v_mov_b32_e32 v112, v2
	v_mov_b32_e32 v113, v2
	v_mov_b32_e32 v82, v2
	v_mov_b32_e32 v83, v2
	v_mov_b32_e32 v84, v2
	v_mov_b32_e32 v85, v2
	v_mov_b32_e32 v90, v2
	v_mov_b32_e32 v91, v2
	v_mov_b32_e32 v92, v2
	v_mov_b32_e32 v93, v2
	v_mov_b32_e32 v98, v2
	v_mov_b32_e32 v99, v2
	v_mov_b32_e32 v100, v2
	v_mov_b32_e32 v101, v2
	v_mov_b32_e32 v106, v2
	v_mov_b32_e32 v107, v2
	v_mov_b32_e32 v108, v2
	v_mov_b32_e32 v109, v2
	v_mov_b32_e32 v114, v2
	v_mov_b32_e32 v115, v2
	v_mov_b32_e32 v116, v2
	v_mov_b32_e32 v117, v2
	v_mov_b32_e32 v118, v2
	v_mov_b32_e32 v119, v2
	v_mov_b32_e32 v120, v2
	v_mov_b32_e32 v121, v2
	v_mov_b32_e32 v122, v2
	v_mov_b32_e32 v123, v2
	v_mov_b32_e32 v124, v2
	v_mov_b32_e32 v125, v2
	v_mov_b32_e32 v126, v2
	v_mov_b32_e32 v127, v2
	v_mov_b32_e32 v128, v2
	v_mov_b32_e32 v129, v2
	v_readlane_b32 s45, v253, 25
	v_readlane_b32 s46, v253, 26
	v_readlane_b32 s47, v253, 27
	v_readlane_b32 s48, v253, 28
	v_readlane_b32 s49, v253, 29
	v_readlane_b32 s50, v253, 30
	v_readlane_b32 s51, v253, 31
	v_readlane_b32 s52, v253, 32
	v_readlane_b32 s53, v253, 33
	v_readlane_b32 s54, v253, 34
	v_readlane_b32 s55, v253, 35
	v_readlane_b32 s56, v253, 36
	v_readlane_b32 s57, v253, 37
	.p2align	6

.LBB0_566:
	s_add_u32 s40, s18, 0x100
	v_mov_b32_e32 v2, 0
	s_addc_u32 s41, s19, 0
	s_mov_b32 s42, -2
	v_mov_b32_e32 v3, v2
	v_mov_b32_e32 v4, v2
	v_mov_b32_e32 v5, v2
	v_mov_b32_e32 v6, v2
	v_mov_b32_e32 v7, v2
	v_mov_b32_e32 v8, v2
	v_mov_b32_e32 v9, v2
	v_mov_b32_e32 v10, v2
	v_mov_b32_e32 v11, v2
	v_mov_b32_e32 v12, v2
	v_mov_b32_e32 v13, v2
	v_mov_b32_e32 v14, v2
	v_mov_b32_e32 v15, v2
	v_mov_b32_e32 v16, v2
	v_mov_b32_e32 v17, v2
	v_mov_b32_e32 v26, v2
	v_mov_b32_e32 v27, v2
	v_mov_b32_e32 v28, v2
	v_mov_b32_e32 v29, v2
	v_mov_b32_e32 v30, v2
	v_mov_b32_e32 v31, v2
	v_mov_b32_e32 v32, v2
	v_mov_b32_e32 v33, v2
	v_mov_b32_e32 v42, v2
	v_mov_b32_e32 v43, v2
	v_mov_b32_e32 v44, v2
	v_mov_b32_e32 v45, v2
	v_mov_b32_e32 v46, v2
	v_mov_b32_e32 v47, v2
	v_mov_b32_e32 v48, v2
	v_mov_b32_e32 v49, v2
	v_mov_b32_e32 v18, v2
	v_mov_b32_e32 v19, v2
	v_mov_b32_e32 v20, v2
	v_mov_b32_e32 v21, v2
	v_mov_b32_e32 v22, v2
	v_mov_b32_e32 v23, v2
	v_mov_b32_e32 v24, v2
	v_mov_b32_e32 v25, v2
	v_mov_b32_e32 v34, v2
	v_mov_b32_e32 v35, v2
	v_mov_b32_e32 v36, v2
	v_mov_b32_e32 v37, v2
	v_mov_b32_e32 v38, v2
	v_mov_b32_e32 v39, v2
	v_mov_b32_e32 v40, v2
	v_mov_b32_e32 v41, v2
	v_mov_b32_e32 v50, v2
	v_mov_b32_e32 v51, v2
	v_mov_b32_e32 v52, v2
	v_mov_b32_e32 v53, v2
	v_mov_b32_e32 v54, v2
	v_mov_b32_e32 v55, v2
	v_mov_b32_e32 v56, v2
	v_mov_b32_e32 v57, v2
	v_mov_b32_e32 v58, v2
	v_mov_b32_e32 v59, v2
	v_mov_b32_e32 v60, v2
	v_mov_b32_e32 v61, v2
	v_mov_b32_e32 v62, v2
	v_mov_b32_e32 v63, v2
	v_mov_b32_e32 v64, v2
	v_mov_b32_e32 v65, v2
	v_mov_b32_e32 v66, v2
	v_mov_b32_e32 v67, v2
	v_mov_b32_e32 v68, v2
	v_mov_b32_e32 v69, v2
	v_mov_b32_e32 v70, v2
	v_mov_b32_e32 v71, v2
	v_mov_b32_e32 v72, v2
	v_mov_b32_e32 v73, v2
	v_mov_b32_e32 v74, v2
	v_mov_b32_e32 v75, v2
	v_mov_b32_e32 v76, v2
	v_mov_b32_e32 v77, v2
	v_mov_b32_e32 v78, v2
	v_mov_b32_e32 v79, v2
	v_mov_b32_e32 v80, v2
	v_mov_b32_e32 v81, v2
	v_mov_b32_e32 v90, v2
	v_mov_b32_e32 v91, v2
	v_mov_b32_e32 v92, v2
	v_mov_b32_e32 v93, v2
	v_mov_b32_e32 v94, v2
	v_mov_b32_e32 v95, v2
	v_mov_b32_e32 v96, v2
	v_mov_b32_e32 v97, v2
	v_mov_b32_e32 v106, v2
	v_mov_b32_e32 v107, v2
	v_mov_b32_e32 v108, v2
	v_mov_b32_e32 v109, v2
	v_mov_b32_e32 v110, v2
	v_mov_b32_e32 v111, v2
	v_mov_b32_e32 v112, v2
	v_mov_b32_e32 v113, v2
	v_mov_b32_e32 v82, v2
	v_mov_b32_e32 v83, v2
	v_mov_b32_e32 v84, v2
	v_mov_b32_e32 v85, v2
	v_mov_b32_e32 v86, v2
	v_mov_b32_e32 v87, v2
	v_mov_b32_e32 v88, v2
	v_mov_b32_e32 v89, v2
	v_mov_b32_e32 v98, v2
	v_mov_b32_e32 v99, v2
	v_mov_b32_e32 v100, v2
	v_mov_b32_e32 v101, v2
	v_mov_b32_e32 v102, v2
	v_mov_b32_e32 v103, v2
	v_mov_b32_e32 v104, v2
	v_mov_b32_e32 v105, v2
	v_mov_b32_e32 v114, v2
	v_mov_b32_e32 v115, v2
	v_mov_b32_e32 v116, v2
	v_mov_b32_e32 v117, v2
	v_mov_b32_e32 v118, v2
	v_mov_b32_e32 v119, v2
	v_mov_b32_e32 v120, v2
	v_mov_b32_e32 v121, v2
	v_mov_b32_e32 v122, v2
	v_mov_b32_e32 v123, v2
	v_mov_b32_e32 v124, v2
	v_mov_b32_e32 v125, v2
	v_mov_b32_e32 v126, v2
	v_mov_b32_e32 v127, v2
	v_mov_b32_e32 v128, v2
	v_mov_b32_e32 v129, v2
	.p2align	6

.LBB0_582:
	s_ashr_i32 s21, s20, 31
	v_readlane_b32 s48, v254, 28
	s_lshl_b64 s[22:23], s[20:21], 17
	v_readlane_b32 s50, v254, 30
	v_readlane_b32 s51, v254, 31
	s_add_u32 s22, s50, s22
	s_addc_u32 s23, s51, s23
	v_readlane_b32 s49, v254, 29
	v_readlane_b32 s52, v254, 32
	v_readlane_b32 s53, v254, 33
	v_readlane_b32 s54, v254, 34
	v_readlane_b32 s55, v254, 35
	v_readlane_b32 s56, v254, 36
	v_readlane_b32 s57, v254, 37
	v_readlane_b32 s58, v254, 38
	v_readlane_b32 s59, v254, 39
	v_readlane_b32 s60, v254, 40
	v_readlane_b32 s61, v254, 41
	v_readlane_b32 s62, v254, 42
	v_readlane_b32 s63, v254, 43
	s_and_b64 s[24:25], s[0:1], exec
	s_cselect_b32 s21, s23, s17
	s_cselect_b32 s45, s22, s16
	s_ashr_i32 s19, s18, 31
	v_readlane_b32 s48, v253, 24
	s_lshl_b64 s[24:25], s[18:19], 17
	v_readlane_b32 s56, v253, 32
	v_readlane_b32 s57, v253, 33
	s_add_u32 s24, s56, s24
	s_addc_u32 s25, s57, s25
	s_and_b64 s[26:27], s[0:1], exec
	v_mov_b32_e32 v2, 0
	s_cselect_b32 s19, s25, s15
	s_cselect_b32 s46, s24, s14
	s_mov_b32 s30, 0
	s_mov_b64 s[26:27], -1
	s_mov_b64 s[28:29], 0
	v_mov_b32_e32 v3, v2
	v_mov_b32_e32 v4, v2
	v_mov_b32_e32 v5, v2
	v_mov_b32_e32 v6, v2
	v_mov_b32_e32 v7, v2
	v_mov_b32_e32 v8, v2
	v_mov_b32_e32 v9, v2
	v_mov_b32_e32 v10, v2
	v_mov_b32_e32 v11, v2
	v_mov_b32_e32 v12, v2
	v_mov_b32_e32 v13, v2
	v_mov_b32_e32 v14, v2
	v_mov_b32_e32 v15, v2
	v_mov_b32_e32 v16, v2
	v_mov_b32_e32 v17, v2
	v_mov_b32_e32 v26, v2
	v_mov_b32_e32 v27, v2
	v_mov_b32_e32 v28, v2
	v_mov_b32_e32 v29, v2
	v_mov_b32_e32 v30, v2
	v_mov_b32_e32 v31, v2
	v_mov_b32_e32 v32, v2
	v_mov_b32_e32 v33, v2
	v_mov_b32_e32 v42, v2
	v_mov_b32_e32 v43, v2
	v_mov_b32_e32 v44, v2
	v_mov_b32_e32 v45, v2
	v_mov_b32_e32 v46, v2
	v_mov_b32_e32 v47, v2
	v_mov_b32_e32 v48, v2
	v_mov_b32_e32 v49, v2
	v_mov_b32_e32 v18, v2
	v_mov_b32_e32 v19, v2
	v_mov_b32_e32 v20, v2
	v_mov_b32_e32 v21, v2
	v_mov_b32_e32 v22, v2
	v_mov_b32_e32 v23, v2
	v_mov_b32_e32 v24, v2
	v_mov_b32_e32 v25, v2
	v_mov_b32_e32 v34, v2
	v_mov_b32_e32 v35, v2
	v_mov_b32_e32 v36, v2
	v_mov_b32_e32 v37, v2
	v_mov_b32_e32 v38, v2
	v_mov_b32_e32 v39, v2
	v_mov_b32_e32 v40, v2
	v_mov_b32_e32 v41, v2
	v_mov_b32_e32 v50, v2
	v_mov_b32_e32 v51, v2
	v_mov_b32_e32 v52, v2
	v_mov_b32_e32 v53, v2
	v_mov_b32_e32 v54, v2
	v_mov_b32_e32 v55, v2
	v_mov_b32_e32 v56, v2
	v_mov_b32_e32 v57, v2
	v_mov_b32_e32 v58, v2
	v_mov_b32_e32 v59, v2
	v_mov_b32_e32 v60, v2
	v_mov_b32_e32 v61, v2
	v_mov_b32_e32 v62, v2
	v_mov_b32_e32 v63, v2
	v_mov_b32_e32 v64, v2
	v_mov_b32_e32 v65, v2
	v_mov_b32_e32 v66, v2
	v_mov_b32_e32 v67, v2
	v_mov_b32_e32 v68, v2
	v_mov_b32_e32 v69, v2
	v_mov_b32_e32 v70, v2
	v_mov_b32_e32 v71, v2
	v_mov_b32_e32 v72, v2
	v_mov_b32_e32 v73, v2
	v_mov_b32_e32 v74, v2
	v_mov_b32_e32 v75, v2
	v_mov_b32_e32 v76, v2
	v_mov_b32_e32 v77, v2
	v_mov_b32_e32 v78, v2
	v_mov_b32_e32 v79, v2
	v_mov_b32_e32 v80, v2
	v_mov_b32_e32 v81, v2
	v_mov_b32_e32 v90, v2
	v_mov_b32_e32 v91, v2
	v_mov_b32_e32 v92, v2
	v_mov_b32_e32 v93, v2
	v_mov_b32_e32 v94, v2
	v_mov_b32_e32 v95, v2
	v_mov_b32_e32 v96, v2
	v_mov_b32_e32 v97, v2
	v_mov_b32_e32 v106, v2
	v_mov_b32_e32 v107, v2
	v_mov_b32_e32 v108, v2
	v_mov_b32_e32 v109, v2
	v_mov_b32_e32 v110, v2
	v_mov_b32_e32 v111, v2
	v_mov_b32_e32 v112, v2
	v_mov_b32_e32 v113, v2
	v_mov_b32_e32 v82, v2
	v_mov_b32_e32 v83, v2
	v_mov_b32_e32 v84, v2
	v_mov_b32_e32 v85, v2
	v_mov_b32_e32 v86, v2
	v_mov_b32_e32 v87, v2
	v_mov_b32_e32 v88, v2
	v_mov_b32_e32 v89, v2
	v_mov_b32_e32 v98, v2
	v_mov_b32_e32 v99, v2
	v_mov_b32_e32 v100, v2
	v_mov_b32_e32 v101, v2
	v_mov_b32_e32 v102, v2
	v_mov_b32_e32 v103, v2
	v_mov_b32_e32 v104, v2
	v_mov_b32_e32 v105, v2
	v_mov_b32_e32 v114, v2
	v_mov_b32_e32 v115, v2
	v_mov_b32_e32 v116, v2
	v_mov_b32_e32 v117, v2
	v_mov_b32_e32 v118, v2
	v_mov_b32_e32 v119, v2
	v_mov_b32_e32 v120, v2
	v_mov_b32_e32 v121, v2
	v_mov_b32_e32 v122, v2
	v_mov_b32_e32 v123, v2
	v_mov_b32_e32 v124, v2
	v_mov_b32_e32 v125, v2
	v_mov_b32_e32 v126, v2
	v_mov_b32_e32 v127, v2
	v_mov_b32_e32 v128, v2
	v_mov_b32_e32 v129, v2
	v_readlane_b32 s49, v253, 25
	v_readlane_b32 s50, v253, 26
	v_readlane_b32 s51, v253, 27
	v_readlane_b32 s52, v253, 28
	v_readlane_b32 s53, v253, 29
	v_readlane_b32 s54, v253, 30
	v_readlane_b32 s55, v253, 31
	v_readlane_b32 s58, v253, 34
	v_readlane_b32 s59, v253, 35
	v_readlane_b32 s60, v253, 36
	v_readlane_b32 s61, v253, 37
	v_readlane_b32 s62, v253, 38
	v_readlane_b32 s63, v253, 39
	.p2align	6

.LBB0_1032:
	s_ashr_i32 s17, s16, 31
	s_lshl_b64 s[10:11], s[16:17], 19
	v_readlane_b32 s52, v254, 44
	v_readlane_b32 s53, v254, 45
	s_add_u32 s18, s52, s10
	s_addc_u32 s19, s53, s11
	v_readlane_b32 s54, v254, 46
	v_readlane_b32 s55, v254, 47
	v_readlane_b32 s56, v254, 48
	v_readlane_b32 s57, v254, 49
	v_readlane_b32 s58, v254, 50
	v_readlane_b32 s59, v254, 51
	v_readlane_b32 s60, v254, 52
	v_readlane_b32 s61, v254, 53
	v_readlane_b32 s62, v254, 54
	v_readlane_b32 s63, v254, 55
	v_readlane_b32 s64, v254, 56
	v_readlane_b32 s65, v254, 57
	v_readlane_b32 s66, v254, 58
	v_readlane_b32 s67, v254, 59
	s_and_b64 s[10:11], s[8:9], exec
	s_cselect_b32 s10, s19, s27
	s_cselect_b32 s11, s18, s26
	s_ashr_i32 s15, s14, 31
	v_readlane_b32 s52, v253, 24
	s_lshl_b64 s[20:21], s[14:15], 19
	v_readlane_b32 s62, v253, 34
	v_readlane_b32 s63, v253, 35
	s_add_u32 s20, s62, s20
	s_addc_u32 s21, s63, s21
	s_and_b64 s[30:31], s[8:9], exec
	s_cselect_b32 s15, s21, s29
	s_cselect_b32 s17, s20, s28
	s_add_u32 s26, s26, 0x40080
	s_addc_u32 s27, s27, 0
	s_add_u32 s23, s28, 0x100
	v_mov_b32_e32 v2, 0
	s_addc_u32 s42, s29, 0
	s_mov_b32 s43, -2
	v_mov_b32_e32 v3, v2
	v_mov_b32_e32 v4, v2
	v_mov_b32_e32 v5, v2
	v_mov_b32_e32 v6, v2
	v_mov_b32_e32 v7, v2
	v_mov_b32_e32 v8, v2
	v_mov_b32_e32 v9, v2
	v_mov_b32_e32 v10, v2
	v_mov_b32_e32 v11, v2
	v_mov_b32_e32 v12, v2
	v_mov_b32_e32 v13, v2
	s_waitcnt vmcnt(0)
	v_mov_b32_e32 v18, v2
	v_mov_b32_e32 v19, v2
	v_mov_b32_e32 v20, v2
	v_mov_b32_e32 v21, v2
	v_mov_b32_e32 v26, v2
	v_mov_b32_e32 v27, v2
	v_mov_b32_e32 v28, v2
	v_mov_b32_e32 v29, v2
	v_mov_b32_e32 v38, v2
	v_mov_b32_e32 v39, v2
	v_mov_b32_e32 v40, v2
	v_mov_b32_e32 v41, v2
	v_mov_b32_e32 v42, v2
	v_mov_b32_e32 v43, v2
	v_mov_b32_e32 v44, v2
	v_mov_b32_e32 v45, v2
	v_mov_b32_e32 v46, v2
	v_mov_b32_e32 v47, v2
	v_mov_b32_e32 v48, v2
	v_mov_b32_e32 v49, v2
	v_mov_b32_e32 v14, v2
	v_mov_b32_e32 v15, v2
	v_mov_b32_e32 v16, v2
	v_mov_b32_e32 v17, v2
	v_mov_b32_e32 v22, v2
	v_mov_b32_e32 v23, v2
	v_mov_b32_e32 v24, v2
	v_mov_b32_e32 v25, v2
	v_mov_b32_e32 v30, v2
	v_mov_b32_e32 v31, v2
	v_mov_b32_e32 v32, v2
	v_mov_b32_e32 v33, v2
	v_mov_b32_e32 v34, v2
	v_mov_b32_e32 v35, v2
	v_mov_b32_e32 v36, v2
	v_mov_b32_e32 v37, v2
	v_mov_b32_e32 v50, v2
	v_mov_b32_e32 v51, v2
	v_mov_b32_e32 v52, v2
	v_mov_b32_e32 v53, v2
	v_mov_b32_e32 v54, v2
	v_mov_b32_e32 v55, v2
	v_mov_b32_e32 v56, v2
	v_mov_b32_e32 v57, v2
	v_mov_b32_e32 v58, v2
	v_mov_b32_e32 v59, v2
	v_mov_b32_e32 v60, v2
	v_mov_b32_e32 v61, v2
	v_mov_b32_e32 v62, v2
	v_mov_b32_e32 v63, v2
	v_mov_b32_e32 v64, v2
	v_mov_b32_e32 v65, v2
	v_mov_b32_e32 v66, v2
	v_mov_b32_e32 v67, v2
	v_mov_b32_e32 v68, v2
	v_mov_b32_e32 v69, v2
	v_mov_b32_e32 v70, v2
	v_mov_b32_e32 v71, v2
	v_mov_b32_e32 v72, v2
	v_mov_b32_e32 v73, v2
	v_mov_b32_e32 v74, v2
	v_mov_b32_e32 v75, v2
	v_mov_b32_e32 v76, v2
	v_mov_b32_e32 v77, v2
	v_mov_b32_e32 v82, v2
	v_mov_b32_e32 v83, v2
	v_mov_b32_e32 v84, v2
	v_mov_b32_e32 v85, v2
	v_mov_b32_e32 v90, v2
	v_mov_b32_e32 v91, v2
	v_mov_b32_e32 v92, v2
	v_mov_b32_e32 v93, v2
	v_mov_b32_e32 v98, v2
	v_mov_b32_e32 v99, v2
	v_mov_b32_e32 v100, v2
	v_mov_b32_e32 v101, v2
	v_mov_b32_e32 v110, v2
	v_mov_b32_e32 v111, v2
	v_mov_b32_e32 v112, v2
	v_mov_b32_e32 v113, v2
	v_mov_b32_e32 v114, v2
	v_mov_b32_e32 v115, v2
	v_mov_b32_e32 v116, v2
	v_mov_b32_e32 v117, v2
	v_mov_b32_e32 v78, v2
	v_mov_b32_e32 v79, v2
	v_mov_b32_e32 v80, v2
	v_mov_b32_e32 v81, v2
	v_mov_b32_e32 v86, v2
	v_mov_b32_e32 v87, v2
	v_mov_b32_e32 v88, v2
	v_mov_b32_e32 v89, v2
	v_mov_b32_e32 v94, v2
	v_mov_b32_e32 v95, v2
	v_mov_b32_e32 v96, v2
	v_mov_b32_e32 v97, v2
	v_mov_b32_e32 v102, v2
	v_mov_b32_e32 v103, v2
	v_mov_b32_e32 v104, v2
	v_mov_b32_e32 v105, v2
	v_mov_b32_e32 v106, v2
	v_mov_b32_e32 v107, v2
	v_mov_b32_e32 v108, v2
	v_mov_b32_e32 v109, v2
	v_mov_b32_e32 v118, v2
	v_mov_b32_e32 v119, v2
	v_mov_b32_e32 v120, v2
	v_mov_b32_e32 v121, v2
	v_mov_b32_e32 v122, v2
	v_mov_b32_e32 v123, v2
	v_mov_b32_e32 v124, v2
	v_mov_b32_e32 v125, v2
	v_mov_b32_e32 v126, v2
	v_mov_b32_e32 v127, v2
	v_mov_b32_e32 v128, v2
	v_mov_b32_e32 v129, v2
	v_readlane_b32 s53, v253, 25
	v_readlane_b32 s54, v253, 26
	v_readlane_b32 s55, v253, 27
	v_readlane_b32 s56, v253, 28
	v_readlane_b32 s57, v253, 29
	v_readlane_b32 s58, v253, 30
	v_readlane_b32 s59, v253, 31
	v_readlane_b32 s60, v253, 32
	v_readlane_b32 s61, v253, 33
	v_readlane_b32 s64, v253, 36
	v_readlane_b32 s65, v253, 37
	v_readlane_b32 s66, v253, 38
	v_readlane_b32 s67, v253, 39
	.p2align	6

.LBB0_1133:
	s_ashr_i32 s25, s24, 31
	v_readlane_b32 s48, v255, 1
	s_lshl_b64 s[10:11], s[24:25], 19
	v_readlane_b32 s54, v255, 7
	v_readlane_b32 s55, v255, 8
	s_add_u32 s26, s54, s10
	s_addc_u32 s27, s55, s11
	v_readlane_b32 s49, v255, 2
	v_readlane_b32 s50, v255, 3
	v_readlane_b32 s51, v255, 4
	v_readlane_b32 s52, v255, 5
	v_readlane_b32 s53, v255, 6
	v_readlane_b32 s56, v255, 9
	v_readlane_b32 s57, v255, 10
	v_readlane_b32 s58, v255, 11
	v_readlane_b32 s59, v255, 12
	v_readlane_b32 s60, v255, 13
	v_readlane_b32 s61, v255, 14
	v_readlane_b32 s62, v255, 15
	v_readlane_b32 s63, v255, 16
	s_and_b64 s[10:11], s[0:1], exec
	s_cselect_b32 s3, s27, s13
	s_cselect_b32 s10, s26, s12
	s_ashr_i32 s23, s22, 31
	v_readlane_b32 s48, v253, 24
	s_lshl_b64 s[28:29], s[22:23], 19
	v_readlane_b32 s60, v253, 36
	v_readlane_b32 s61, v253, 37
	s_add_u32 s28, s60, s28
	s_addc_u32 s29, s61, s29
	s_and_b64 s[34:35], s[0:1], exec
	s_cselect_b32 s11, s29, s31
	s_cselect_b32 s23, s28, s30
	s_add_u32 s12, s12, 0x40080
	s_addc_u32 s13, s13, 0
	s_add_u32 s25, s30, 0x100
	v_mov_b32_e32 v2, 0
	s_addc_u32 s47, s31, 0
	s_mov_b32 s48, -2
	v_mov_b32_e32 v3, v2
	v_mov_b32_e32 v4, v2
	v_mov_b32_e32 v5, v2
	v_mov_b32_e32 v6, v2
	v_mov_b32_e32 v7, v2
	v_mov_b32_e32 v8, v2
	v_mov_b32_e32 v9, v2
	v_mov_b32_e32 v10, v2
	v_mov_b32_e32 v11, v2
	v_mov_b32_e32 v12, v2
	v_mov_b32_e32 v13, v2
	s_waitcnt vmcnt(0)
	v_mov_b32_e32 v18, v2
	v_mov_b32_e32 v19, v2
	v_mov_b32_e32 v20, v2
	v_mov_b32_e32 v21, v2
	v_mov_b32_e32 v26, v2
	v_mov_b32_e32 v27, v2
	v_mov_b32_e32 v28, v2
	v_mov_b32_e32 v29, v2
	v_mov_b32_e32 v34, v2
	v_mov_b32_e32 v35, v2
	v_mov_b32_e32 v36, v2
	v_mov_b32_e32 v37, v2
	v_mov_b32_e32 v42, v2
	v_mov_b32_e32 v43, v2
	v_mov_b32_e32 v44, v2
	v_mov_b32_e32 v45, v2
	v_mov_b32_e32 v50, v2
	v_mov_b32_e32 v51, v2
	v_mov_b32_e32 v52, v2
	v_mov_b32_e32 v53, v2
	v_mov_b32_e32 v14, v2
	v_mov_b32_e32 v15, v2
	v_mov_b32_e32 v16, v2
	v_mov_b32_e32 v17, v2
	v_mov_b32_e32 v22, v2
	v_mov_b32_e32 v23, v2
	v_mov_b32_e32 v24, v2
	v_mov_b32_e32 v25, v2
	v_mov_b32_e32 v30, v2
	v_mov_b32_e32 v31, v2
	v_mov_b32_e32 v32, v2
	v_mov_b32_e32 v33, v2
	v_mov_b32_e32 v38, v2
	v_mov_b32_e32 v39, v2
	v_mov_b32_e32 v40, v2
	v_mov_b32_e32 v41, v2
	v_mov_b32_e32 v46, v2
	v_mov_b32_e32 v47, v2
	v_mov_b32_e32 v48, v2
	v_mov_b32_e32 v49, v2
	v_mov_b32_e32 v54, v2
	v_mov_b32_e32 v55, v2
	v_mov_b32_e32 v56, v2
	v_mov_b32_e32 v57, v2
	v_mov_b32_e32 v58, v2
	v_mov_b32_e32 v59, v2
	v_mov_b32_e32 v60, v2
	v_mov_b32_e32 v61, v2
	v_mov_b32_e32 v62, v2
	v_mov_b32_e32 v63, v2
	v_mov_b32_e32 v64, v2
	v_mov_b32_e32 v65, v2
	v_mov_b32_e32 v66, v2
	v_mov_b32_e32 v67, v2
	v_mov_b32_e32 v68, v2
	v_mov_b32_e32 v69, v2
	v_mov_b32_e32 v70, v2
	v_mov_b32_e32 v71, v2
	v_mov_b32_e32 v72, v2
	v_mov_b32_e32 v73, v2
	v_mov_b32_e32 v74, v2
	v_mov_b32_e32 v75, v2
	v_mov_b32_e32 v76, v2
	v_mov_b32_e32 v77, v2
	v_mov_b32_e32 v82, v2
	v_mov_b32_e32 v83, v2
	v_mov_b32_e32 v84, v2
	v_mov_b32_e32 v85, v2
	v_mov_b32_e32 v90, v2
	v_mov_b32_e32 v91, v2
	v_mov_b32_e32 v92, v2
	v_mov_b32_e32 v93, v2
	v_mov_b32_e32 v98, v2
	v_mov_b32_e32 v99, v2
	v_mov_b32_e32 v100, v2
	v_mov_b32_e32 v101, v2
	v_mov_b32_e32 v106, v2
	v_mov_b32_e32 v107, v2
	v_mov_b32_e32 v108, v2
	v_mov_b32_e32 v109, v2
	v_mov_b32_e32 v114, v2
	v_mov_b32_e32 v115, v2
	v_mov_b32_e32 v116, v2
	v_mov_b32_e32 v117, v2
	v_mov_b32_e32 v78, v2
	v_mov_b32_e32 v79, v2
	v_mov_b32_e32 v80, v2
	v_mov_b32_e32 v81, v2
	v_mov_b32_e32 v86, v2
	v_mov_b32_e32 v87, v2
	v_mov_b32_e32 v88, v2
	v_mov_b32_e32 v89, v2
	v_mov_b32_e32 v94, v2
	v_mov_b32_e32 v95, v2
	v_mov_b32_e32 v96, v2
	v_mov_b32_e32 v97, v2
	v_mov_b32_e32 v102, v2
	v_mov_b32_e32 v103, v2
	v_mov_b32_e32 v104, v2
	v_mov_b32_e32 v105, v2
	v_mov_b32_e32 v110, v2
	v_mov_b32_e32 v111, v2
	v_mov_b32_e32 v112, v2
	v_mov_b32_e32 v113, v2
	v_mov_b32_e32 v118, v2
	v_mov_b32_e32 v119, v2
	v_mov_b32_e32 v120, v2
	v_mov_b32_e32 v121, v2
	v_mov_b32_e32 v122, v2
	v_mov_b32_e32 v123, v2
	v_mov_b32_e32 v124, v2
	v_mov_b32_e32 v125, v2
	v_mov_b32_e32 v126, v2
	v_mov_b32_e32 v127, v2
	v_mov_b32_e32 v128, v2
	v_mov_b32_e32 v129, v2
	v_readlane_b32 s49, v253, 25
	v_readlane_b32 s50, v253, 26
	v_readlane_b32 s51, v253, 27
	v_readlane_b32 s52, v253, 28
	v_readlane_b32 s53, v253, 29
	v_readlane_b32 s54, v253, 30
	v_readlane_b32 s55, v253, 31
	v_readlane_b32 s56, v253, 32
	v_readlane_b32 s57, v253, 33
	v_readlane_b32 s58, v253, 34
	v_readlane_b32 s59, v253, 35
	v_readlane_b32 s62, v253, 38
	v_readlane_b32 s63, v253, 39
	.p2align	6

.LBB0_1298:
	s_ashr_i32 s21, s20, 31
	s_lshl_b64 s[10:11], s[20:21], 18
	s_add_u32 s22, s68, s10
	s_addc_u32 s23, s69, s11
	s_and_b64 s[10:11], s[4:5], exec
	s_cselect_b32 s10, s23, s29
	s_cselect_b32 s11, s22, s28
	s_ashr_i32 s19, s18, 31
	s_lshl_b64 s[24:25], s[18:19], 18
	v_readlane_b32 s48, v255, 1
	v_readlane_b32 s49, v255, 2
	s_add_u32 s24, s48, s24
	s_addc_u32 s25, s49, s25
	s_and_b64 s[34:35], s[4:5], exec
	s_cselect_b32 s19, s25, s31
	s_cselect_b32 s21, s24, s30
	s_add_u32 s28, s28, 0x20080
	s_addc_u32 s29, s29, 0
	s_add_u32 s27, s30, 0x100
	v_mov_b32_e32 v2, 0
	s_addc_u32 s48, s31, 0
	s_mov_b32 s49, -2
	v_mov_b32_e32 v3, v2
	v_mov_b32_e32 v4, v2
	v_mov_b32_e32 v5, v2
	v_mov_b32_e32 v6, v2
	v_mov_b32_e32 v7, v2
	v_mov_b32_e32 v8, v2
	v_mov_b32_e32 v9, v2
	s_waitcnt vmcnt(0)
	v_mov_b32_e32 v18, v2
	v_mov_b32_e32 v19, v2
	v_mov_b32_e32 v20, v2
	v_mov_b32_e32 v21, v2
	v_mov_b32_e32 v22, v2
	v_mov_b32_e32 v23, v2
	v_mov_b32_e32 v24, v2
	v_mov_b32_e32 v25, v2
	v_mov_b32_e32 v34, v2
	v_mov_b32_e32 v35, v2
	v_mov_b32_e32 v36, v2
	v_mov_b32_e32 v37, v2
	v_mov_b32_e32 v38, v2
	v_mov_b32_e32 v39, v2
	v_mov_b32_e32 v40, v2
	v_mov_b32_e32 v41, v2
	v_mov_b32_e32 v50, v2
	v_mov_b32_e32 v51, v2
	v_mov_b32_e32 v52, v2
	v_mov_b32_e32 v53, v2
	v_mov_b32_e32 v54, v2
	v_mov_b32_e32 v55, v2
	v_mov_b32_e32 v56, v2
	v_mov_b32_e32 v57, v2
	v_mov_b32_e32 v10, v2
	v_mov_b32_e32 v11, v2
	v_mov_b32_e32 v12, v2
	v_mov_b32_e32 v13, v2
	v_mov_b32_e32 v14, v2
	v_mov_b32_e32 v15, v2
	v_mov_b32_e32 v16, v2
	v_mov_b32_e32 v17, v2
	v_mov_b32_e32 v26, v2
	v_mov_b32_e32 v27, v2
	v_mov_b32_e32 v28, v2
	v_mov_b32_e32 v29, v2
	v_mov_b32_e32 v30, v2
	v_mov_b32_e32 v31, v2
	v_mov_b32_e32 v32, v2
	v_mov_b32_e32 v33, v2
	v_mov_b32_e32 v42, v2
	v_mov_b32_e32 v43, v2
	v_mov_b32_e32 v44, v2
	v_mov_b32_e32 v45, v2
	v_mov_b32_e32 v46, v2
	v_mov_b32_e32 v47, v2
	v_mov_b32_e32 v48, v2
	v_mov_b32_e32 v49, v2
	v_mov_b32_e32 v58, v2
	v_mov_b32_e32 v59, v2
	v_mov_b32_e32 v60, v2
	v_mov_b32_e32 v61, v2
	v_mov_b32_e32 v62, v2
	v_mov_b32_e32 v63, v2
	v_mov_b32_e32 v64, v2
	v_mov_b32_e32 v65, v2
	v_mov_b32_e32 v66, v2
	v_mov_b32_e32 v67, v2
	v_mov_b32_e32 v68, v2
	v_mov_b32_e32 v69, v2
	v_mov_b32_e32 v70, v2
	v_mov_b32_e32 v71, v2
	v_mov_b32_e32 v72, v2
	v_mov_b32_e32 v73, v2
	v_mov_b32_e32 v82, v2
	v_mov_b32_e32 v83, v2
	v_mov_b32_e32 v84, v2
	v_mov_b32_e32 v85, v2
	v_mov_b32_e32 v86, v2
	v_mov_b32_e32 v87, v2
	v_mov_b32_e32 v88, v2
	v_mov_b32_e32 v89, v2
	v_mov_b32_e32 v98, v2
	v_mov_b32_e32 v99, v2
	v_mov_b32_e32 v100, v2
	v_mov_b32_e32 v101, v2
	v_mov_b32_e32 v102, v2
	v_mov_b32_e32 v103, v2
	v_mov_b32_e32 v104, v2
	v_mov_b32_e32 v105, v2
	v_mov_b32_e32 v126, v2
	v_mov_b32_e32 v127, v2
	v_mov_b32_e32 v128, v2
	v_mov_b32_e32 v129, v2
	v_mov_b32_e32 v130, v2
	v_mov_b32_e32 v131, v2
	v_mov_b32_e32 v132, v2
	v_mov_b32_e32 v133, v2
	v_mov_b32_e32 v74, v2
	v_mov_b32_e32 v75, v2
	v_mov_b32_e32 v76, v2
	v_mov_b32_e32 v77, v2
	v_mov_b32_e32 v78, v2
	v_mov_b32_e32 v79, v2
	v_mov_b32_e32 v80, v2
	v_mov_b32_e32 v81, v2
	v_mov_b32_e32 v90, v2
	v_mov_b32_e32 v91, v2
	v_mov_b32_e32 v92, v2
	v_mov_b32_e32 v93, v2
	v_mov_b32_e32 v94, v2
	v_mov_b32_e32 v95, v2
	v_mov_b32_e32 v96, v2
	v_mov_b32_e32 v97, v2
	v_mov_b32_e32 v110, v2
	v_mov_b32_e32 v111, v2
	v_mov_b32_e32 v112, v2
	v_mov_b32_e32 v113, v2
	v_mov_b32_e32 v114, v2
	v_mov_b32_e32 v115, v2
	v_mov_b32_e32 v116, v2
	v_mov_b32_e32 v117, v2
	v_mov_b32_e32 v150, v2
	v_mov_b32_e32 v151, v2
	v_mov_b32_e32 v152, v2
	v_mov_b32_e32 v153, v2
	v_mov_b32_e32 v154, v2
	v_mov_b32_e32 v155, v2
	v_mov_b32_e32 v156, v2
	v_mov_b32_e32 v157, v2
	v_readlane_b32 s50, v255, 3
	v_readlane_b32 s51, v255, 4
	v_readlane_b32 s52, v255, 5
	v_readlane_b32 s53, v255, 6
	v_readlane_b32 s54, v255, 7
	v_readlane_b32 s55, v255, 8
	v_readlane_b32 s56, v255, 9
	v_readlane_b32 s57, v255, 10
	v_readlane_b32 s58, v255, 11
	v_readlane_b32 s59, v255, 12
	v_readlane_b32 s60, v255, 13
	v_readlane_b32 s61, v255, 14
	v_readlane_b32 s62, v255, 15
	v_readlane_b32 s63, v255, 16
	.p2align	6

.LBB0_1399:
	s_ashr_i32 s25, s24, 31
	v_readlane_b32 s48, v255, 1
	s_lshl_b64 s[10:11], s[24:25], 19
	v_readlane_b32 s56, v255, 9
	v_readlane_b32 s57, v255, 10
	s_add_u32 s26, s56, s10
	s_addc_u32 s27, s57, s11
	s_and_b64 s[10:11], s[0:1], exec
	s_cselect_b32 s3, s27, s5
	s_cselect_b32 s10, s26, s4
	s_ashr_i32 s23, s22, 31
	v_readlane_b32 s50, v255, 3
	s_lshl_b64 s[28:29], s[22:23], 19
	v_readlane_b32 s51, v255, 4
	s_add_u32 s28, s50, s28
	s_addc_u32 s29, s51, s29
	s_and_b64 s[34:35], s[0:1], exec
	s_cselect_b32 s11, s29, s31
	s_cselect_b32 s23, s28, s30
	s_add_u32 s4, s4, 0x40080
	s_addc_u32 s5, s5, 0
	s_add_u32 s25, s30, 0x100
	v_mov_b32_e32 v2, 0
	s_addc_u32 s47, s31, 0
	s_mov_b32 s48, -2
	v_mov_b32_e32 v3, v2
	v_mov_b32_e32 v4, v2
	v_mov_b32_e32 v5, v2
	v_mov_b32_e32 v6, v2
	v_mov_b32_e32 v7, v2
	v_mov_b32_e32 v8, v2
	v_mov_b32_e32 v9, v2
	v_mov_b32_e32 v18, v2
	v_mov_b32_e32 v19, v2
	v_mov_b32_e32 v20, v2
	v_mov_b32_e32 v21, v2
	s_waitcnt vmcnt(0)
	v_mov_b32_e32 v22, v2
	v_mov_b32_e32 v23, v2
	v_mov_b32_e32 v24, v2
	v_mov_b32_e32 v25, v2
	v_mov_b32_e32 v34, v2
	v_mov_b32_e32 v35, v2
	v_mov_b32_e32 v36, v2
	v_mov_b32_e32 v37, v2
	v_mov_b32_e32 v38, v2
	v_mov_b32_e32 v39, v2
	v_mov_b32_e32 v40, v2
	v_mov_b32_e32 v41, v2
	v_mov_b32_e32 v50, v2
	v_mov_b32_e32 v51, v2
	v_mov_b32_e32 v52, v2
	v_mov_b32_e32 v53, v2
	v_mov_b32_e32 v54, v2
	v_mov_b32_e32 v55, v2
	v_mov_b32_e32 v56, v2
	v_mov_b32_e32 v57, v2
	v_mov_b32_e32 v10, v2
	v_mov_b32_e32 v11, v2
	v_mov_b32_e32 v12, v2
	v_mov_b32_e32 v13, v2
	v_mov_b32_e32 v14, v2
	v_mov_b32_e32 v15, v2
	v_mov_b32_e32 v16, v2
	v_mov_b32_e32 v17, v2
	v_mov_b32_e32 v26, v2
	v_mov_b32_e32 v27, v2
	v_mov_b32_e32 v28, v2
	v_mov_b32_e32 v29, v2
	v_mov_b32_e32 v30, v2
	v_mov_b32_e32 v31, v2
	v_mov_b32_e32 v32, v2
	v_mov_b32_e32 v33, v2
	v_mov_b32_e32 v42, v2
	v_mov_b32_e32 v43, v2
	v_mov_b32_e32 v44, v2
	v_mov_b32_e32 v45, v2
	v_mov_b32_e32 v46, v2
	v_mov_b32_e32 v47, v2
	v_mov_b32_e32 v48, v2
	v_mov_b32_e32 v49, v2
	v_mov_b32_e32 v58, v2
	v_mov_b32_e32 v59, v2
	v_mov_b32_e32 v60, v2
	v_mov_b32_e32 v61, v2
	v_mov_b32_e32 v62, v2
	v_mov_b32_e32 v63, v2
	v_mov_b32_e32 v64, v2
	v_mov_b32_e32 v65, v2
	v_mov_b32_e32 v66, v2
	v_mov_b32_e32 v67, v2
	v_mov_b32_e32 v68, v2
	v_mov_b32_e32 v69, v2
	v_mov_b32_e32 v70, v2
	v_mov_b32_e32 v71, v2
	v_mov_b32_e32 v72, v2
	v_mov_b32_e32 v73, v2
	v_mov_b32_e32 v82, v2
	v_mov_b32_e32 v83, v2
	v_mov_b32_e32 v84, v2
	v_mov_b32_e32 v85, v2
	v_mov_b32_e32 v86, v2
	v_mov_b32_e32 v87, v2
	v_mov_b32_e32 v88, v2
	v_mov_b32_e32 v89, v2
	v_mov_b32_e32 v98, v2
	v_mov_b32_e32 v99, v2
	v_mov_b32_e32 v100, v2
	v_mov_b32_e32 v101, v2
	v_mov_b32_e32 v102, v2
	v_mov_b32_e32 v103, v2
	v_mov_b32_e32 v104, v2
	v_mov_b32_e32 v105, v2
	v_mov_b32_e32 v114, v2
	v_mov_b32_e32 v115, v2
	v_mov_b32_e32 v116, v2
	v_mov_b32_e32 v117, v2
	v_mov_b32_e32 v118, v2
	v_mov_b32_e32 v119, v2
	v_mov_b32_e32 v120, v2
	v_mov_b32_e32 v121, v2
	v_mov_b32_e32 v74, v2
	v_mov_b32_e32 v75, v2
	v_mov_b32_e32 v76, v2
	v_mov_b32_e32 v77, v2
	v_mov_b32_e32 v78, v2
	v_mov_b32_e32 v79, v2
	v_mov_b32_e32 v80, v2
	v_mov_b32_e32 v81, v2
	v_mov_b32_e32 v90, v2
	v_mov_b32_e32 v91, v2
	v_mov_b32_e32 v92, v2
	v_mov_b32_e32 v93, v2
	v_mov_b32_e32 v94, v2
	v_mov_b32_e32 v95, v2
	v_mov_b32_e32 v96, v2
	v_mov_b32_e32 v97, v2
	v_mov_b32_e32 v106, v2
	v_mov_b32_e32 v107, v2
	v_mov_b32_e32 v108, v2
	v_mov_b32_e32 v109, v2
	v_mov_b32_e32 v110, v2
	v_mov_b32_e32 v111, v2
	v_mov_b32_e32 v112, v2
	v_mov_b32_e32 v113, v2
	v_mov_b32_e32 v122, v2
	v_mov_b32_e32 v123, v2
	v_mov_b32_e32 v124, v2
	v_mov_b32_e32 v125, v2
	v_mov_b32_e32 v126, v2
	v_mov_b32_e32 v127, v2
	v_mov_b32_e32 v128, v2
	v_mov_b32_e32 v129, v2
	v_readlane_b32 s49, v255, 2
	v_readlane_b32 s52, v255, 5
	v_readlane_b32 s53, v255, 6
	v_readlane_b32 s54, v255, 7
	v_readlane_b32 s55, v255, 8
	v_readlane_b32 s58, v255, 11
	v_readlane_b32 s59, v255, 12
	v_readlane_b32 s60, v255, 13
	v_readlane_b32 s61, v255, 14
	v_readlane_b32 s62, v255, 15
	v_readlane_b32 s63, v255, 16
	.p2align	6

.LBB0_1484:
	s_ashr_i32 s13, s12, 31
	s_lshl_b64 s[14:15], s[12:13], 21
	s_add_u32 s14, s70, s14
	s_addc_u32 s15, s71, s15
	s_and_b64 s[16:17], s[0:1], exec
	v_readlane_b32 s40, v255, 1
	s_cselect_b32 s13, s15, s21
	s_cselect_b32 s39, s14, s20
	s_ashr_i32 s11, s10, 31
	v_readlane_b32 s41, v255, 2
	v_readlane_b32 s44, v255, 5
	v_readlane_b32 s45, v255, 6
	s_lshl_b64 s[16:17], s[10:11], 21
	s_mov_b64 s[40:41], s[44:45]
	s_add_u32 s16, s40, s16
	s_addc_u32 s17, s41, s17
	s_and_b64 s[24:25], s[0:1], exec
	s_cselect_b32 s11, s17, s23
	s_cselect_b32 s40, s16, s22
	s_add_u32 s20, s20, 0x100080
	s_addc_u32 s21, s21, 0
	v_readlane_b32 s42, v255, 3
	v_readlane_b32 s43, v255, 4
	s_add_u32 s41, s22, 0x100
	v_mov_b32_e32 v2, 0
	s_addc_u32 s42, s23, 0
	s_mov_b32 s43, -2
	v_mov_b32_e32 v3, v2
	v_mov_b32_e32 v4, v2
	v_mov_b32_e32 v5, v2
	v_mov_b32_e32 v6, v2
	v_mov_b32_e32 v7, v2
	v_mov_b32_e32 v8, v2
	v_mov_b32_e32 v9, v2
	v_mov_b32_e32 v14, v2
	v_mov_b32_e32 v15, v2
	v_mov_b32_e32 v16, v2
	v_mov_b32_e32 v17, v2
	s_waitcnt vmcnt(0)
	v_mov_b32_e32 v22, v2
	v_mov_b32_e32 v23, v2
	v_mov_b32_e32 v24, v2
	v_mov_b32_e32 v25, v2
	v_mov_b32_e32 v30, v2
	v_mov_b32_e32 v31, v2
	v_mov_b32_e32 v32, v2
	v_mov_b32_e32 v33, v2
	v_mov_b32_e32 v38, v2
	v_mov_b32_e32 v39, v2
	v_mov_b32_e32 v40, v2
	v_mov_b32_e32 v41, v2
	v_mov_b32_e32 v46, v2
	v_mov_b32_e32 v47, v2
	v_mov_b32_e32 v48, v2
	v_mov_b32_e32 v49, v2
	v_mov_b32_e32 v54, v2
	v_mov_b32_e32 v55, v2
	v_mov_b32_e32 v56, v2
	v_mov_b32_e32 v57, v2
	v_mov_b32_e32 v10, v2
	v_mov_b32_e32 v11, v2
	v_mov_b32_e32 v12, v2
	v_mov_b32_e32 v13, v2
	v_mov_b32_e32 v18, v2
	v_mov_b32_e32 v19, v2
	v_mov_b32_e32 v20, v2
	v_mov_b32_e32 v21, v2
	v_mov_b32_e32 v26, v2
	v_mov_b32_e32 v27, v2
	v_mov_b32_e32 v28, v2
	v_mov_b32_e32 v29, v2
	v_mov_b32_e32 v34, v2
	v_mov_b32_e32 v35, v2
	v_mov_b32_e32 v36, v2
	v_mov_b32_e32 v37, v2
	v_mov_b32_e32 v42, v2
	v_mov_b32_e32 v43, v2
	v_mov_b32_e32 v44, v2
	v_mov_b32_e32 v45, v2
	v_mov_b32_e32 v50, v2
	v_mov_b32_e32 v51, v2
	v_mov_b32_e32 v52, v2
	v_mov_b32_e32 v53, v2
	v_mov_b32_e32 v58, v2
	v_mov_b32_e32 v59, v2
	v_mov_b32_e32 v60, v2
	v_mov_b32_e32 v61, v2
	v_mov_b32_e32 v62, v2
	v_mov_b32_e32 v63, v2
	v_mov_b32_e32 v64, v2
	v_mov_b32_e32 v65, v2
	v_mov_b32_e32 v66, v2
	v_mov_b32_e32 v67, v2
	v_mov_b32_e32 v68, v2
	v_mov_b32_e32 v69, v2
	v_mov_b32_e32 v70, v2
	v_mov_b32_e32 v71, v2
	v_mov_b32_e32 v72, v2
	v_mov_b32_e32 v73, v2
	v_mov_b32_e32 v78, v2
	v_mov_b32_e32 v79, v2
	v_mov_b32_e32 v80, v2
	v_mov_b32_e32 v81, v2
	v_mov_b32_e32 v86, v2
	v_mov_b32_e32 v87, v2
	v_mov_b32_e32 v88, v2
	v_mov_b32_e32 v89, v2
	v_mov_b32_e32 v94, v2
	v_mov_b32_e32 v95, v2
	v_mov_b32_e32 v96, v2
	v_mov_b32_e32 v97, v2
	v_mov_b32_e32 v102, v2
	v_mov_b32_e32 v103, v2
	v_mov_b32_e32 v104, v2
	v_mov_b32_e32 v105, v2
	v_mov_b32_e32 v110, v2
	v_mov_b32_e32 v111, v2
	v_mov_b32_e32 v112, v2
	v_mov_b32_e32 v113, v2
	v_mov_b32_e32 v118, v2
	v_mov_b32_e32 v119, v2
	v_mov_b32_e32 v120, v2
	v_mov_b32_e32 v121, v2
	v_mov_b32_e32 v74, v2
	v_mov_b32_e32 v75, v2
	v_mov_b32_e32 v76, v2
	v_mov_b32_e32 v77, v2
	v_mov_b32_e32 v82, v2
	v_mov_b32_e32 v83, v2
	v_mov_b32_e32 v84, v2
	v_mov_b32_e32 v85, v2
	v_mov_b32_e32 v90, v2
	v_mov_b32_e32 v91, v2
	v_mov_b32_e32 v92, v2
	v_mov_b32_e32 v93, v2
	v_mov_b32_e32 v98, v2
	v_mov_b32_e32 v99, v2
	v_mov_b32_e32 v100, v2
	v_mov_b32_e32 v101, v2
	v_mov_b32_e32 v106, v2
	v_mov_b32_e32 v107, v2
	v_mov_b32_e32 v108, v2
	v_mov_b32_e32 v109, v2
	v_mov_b32_e32 v114, v2
	v_mov_b32_e32 v115, v2
	v_mov_b32_e32 v116, v2
	v_mov_b32_e32 v117, v2
	v_mov_b32_e32 v122, v2
	v_mov_b32_e32 v123, v2
	v_mov_b32_e32 v124, v2
	v_mov_b32_e32 v125, v2
	v_mov_b32_e32 v126, v2
	v_mov_b32_e32 v127, v2
	v_mov_b32_e32 v128, v2
	v_mov_b32_e32 v129, v2
	v_readlane_b32 s46, v255, 7
	v_readlane_b32 s47, v255, 8
	v_readlane_b32 s48, v255, 9
	v_readlane_b32 s49, v255, 10
	v_readlane_b32 s50, v255, 11
	v_readlane_b32 s51, v255, 12
	v_readlane_b32 s52, v255, 13
	v_readlane_b32 s53, v255, 14
	v_readlane_b32 s54, v255, 15
	v_readlane_b32 s55, v255, 16
	.p2align	6
